# sparse attention: last PV MFMAs of a block ride on the next block's bookkeeping, task prologue asks for the block-list word first and requests tiles 1-2 before the q fragments are built, no load drain
# speedup vs baseline: 1.0327x; 1.0059x over previous
.Lnsa_task:
	s_lshr_b32 s65, s26, 8
	s_and_b32 s1, s26, 255
	s_and_b32 s2, s1, 7
	s_lshr_b32 s1, s1, 3
	s_lshl_b32 s2, s2, 5
	s_or_b32 s1, s1, s2
	s_and_b32 s28, s1, 31
	s_sub_i32 s2, 31, s28
	s_bitcmp1_b32 s65, 0
	s_cselect_b32 s28, s2, s28
	s_lshr_b32 s29, s1, 5
	s_lshl_b32 s2, s65, 3
	s_add_i32 s29, s29, s2
	s_lshr_b32 s30, s29, 1
	s_and_b32 s31, s29, 1
	s_lshl_b32 s36, s31, 2
	s_add_i32 s36, s36, s34
	s_lshl_b32 s33, s28, 6
	s_mov_b32 s32, s28
	s_lshl_b32 s2, s35, 5
	s_add_i32 s2, s2, s33
	v_add_u32_e32 v86, s2, v112
	v_add_u32_e32 v87, 16, v86
	s_lshl_b32 s6, s29, 11
	s_add_i32 s7, s6, s33
	v_add_u32_e32 v221, s7, v152
	v_lshlrev_b32_e32 v221, 2, v221
	s_add_u32 s4, s96, 0x2e00000
	s_addc_u32 s5, s97, 0
	global_load_dword v243, v221, s[4:5]
	s_lshl_b32 s3, s30, 11
	v_add_u32_e32 v220, s3, v86
	v_lshlrev_b32_e32 v234, 10, v220
	s_lshl_b32 s4, s36, 7
	v_add_u32_e32 v234, s4, v234
	v_lshl_add_u32 v234, v113, 4, v234
	v_mov_b32_e32 v235, 0
	s_add_u32 s4, s96, 0xe000000
	s_addc_u32 s5, s97, 0
	v_lshl_add_u64 v[234:235], s[4:5], 0, v[234:235]
	global_load_dwordx4 v[160:163], v[234:235], off
	global_load_dwordx4 v[164:167], v[234:235], off offset:64
	v_lshlrev_b32_e32 v236, 8, v86
	v_lshl_add_u32 v236, v113, 6, v236
	s_add_u32 s4, s96, 0x2c00000
	s_addc_u32 s5, s97, 0
	global_load_dwordx4 v[124:127], v236, s[4:5] offset:0
	global_load_dwordx4 v[128:131], v236, s[4:5] offset:16
	global_load_dwordx4 v[132:135], v236, s[4:5] offset:32
	global_load_dwordx4 v[136:139], v236, s[4:5] offset:48
	s_lshl_b32 s6, s29, 11
	v_add_u32_e32 v221, s6, v86
	v_lshlrev_b32_e32 v221, 2, v221
	s_add_u32 s4, s96, 0x2e00000
	s_addc_u32 s5, s97, 0
	global_load_dword v84, v221, s[4:5]
	v_add_u32_e32 v220, s3, v87
	v_lshlrev_b32_e32 v234, 10, v220
	s_lshl_b32 s4, s36, 7
	v_add_u32_e32 v234, s4, v234
	v_lshl_add_u32 v234, v113, 4, v234
	v_mov_b32_e32 v235, 0
	s_add_u32 s4, s96, 0xe000000
	s_addc_u32 s5, s97, 0
	v_lshl_add_u64 v[234:235], s[4:5], 0, v[234:235]
	global_load_dwordx4 v[168:171], v[234:235], off
	global_load_dwordx4 v[172:175], v[234:235], off offset:64
	v_lshlrev_b32_e32 v236, 8, v87
	v_lshl_add_u32 v236, v113, 6, v236
	s_add_u32 s4, s96, 0x2c00000
	s_addc_u32 s5, s97, 0
	global_load_dwordx4 v[140:143], v236, s[4:5] offset:0
	global_load_dwordx4 v[144:147], v236, s[4:5] offset:16
	global_load_dwordx4 v[148:151], v236, s[4:5] offset:32
	global_load_dwordx4 v[154:157], v236, s[4:5] offset:48
	s_lshl_b32 s6, s29, 11
	v_add_u32_e32 v221, s6, v87
	v_lshlrev_b32_e32 v221, 2, v221
	s_add_u32 s4, s96, 0x2e00000
	s_addc_u32 s5, s97, 0
	global_load_dword v85, v221, s[4:5]
	s_lshl_b32 s3, s30, 11
	s_mul_i32 s2, s36, 6
	s_add_i32 s2, s2, 2
	s_add_u32 s8, s96, 0x13000000
	s_addc_u32 s9, s97, 0
	v_add_u32_e32 v223, s3, v86
	v_lshlrev_b32_e32 v223, 6, v223
	v_add_u32_e32 v223, s2, v223
	global_load_ushort v119, v223, s[8:9]
	global_load_ushort v158, v223, s[8:9] offset:2
	v_add_u32_e32 v223, s3, v87
	v_lshlrev_b32_e32 v223, 6, v223
	v_add_u32_e32 v223, s2, v223
	global_load_ushort v159, v223, s[8:9]
	global_load_ushort v233, v223, s[8:9] offset:2
	s_add_u32 s8, s96, 0x9000000
	s_addc_u32 s9, s97, 0
	v_add_u32_e32 v223, s3, v86
	v_lshlrev_b32_e32 v223, 10, v223
	s_lshl_b32 s2, s36, 7
	v_add_u32_e32 v223, s2, v223
	v_lshl_add_u32 v223, v113, 3, v223
	global_load_dwordx2 v[16:17], v223, s[8:9] offset:0
	global_load_dwordx2 v[20:21], v223, s[8:9] offset:32
	global_load_dwordx2 v[24:25], v223, s[8:9] offset:64
	global_load_dwordx2 v[28:29], v223, s[8:9] offset:96
	v_add_u32_e32 v223, s3, v87
	v_lshlrev_b32_e32 v223, 10, v223
	s_lshl_b32 s2, s36, 7
	v_add_u32_e32 v223, s2, v223
	v_lshl_add_u32 v223, v113, 3, v223
	global_load_dwordx2 v[32:33], v223, s[8:9] offset:0
	global_load_dwordx2 v[36:37], v223, s[8:9] offset:32
	global_load_dwordx2 v[40:41], v223, s[8:9] offset:64
	global_load_dwordx2 v[44:45], v223, s[8:9] offset:96
	s_mul_i32 s2, s30, 0x300000
	s_add_u32 s8, s96, 0x10000000
	s_addc_u32 s9, s97, 0
	s_add_u32 s8, s8, s2
	s_addc_u32 s9, s9, 0
	s_lshl_b32 s2, s31, 7
	s_add_u32 s8, s8, s2
	s_addc_u32 s9, s9, 0
	s_add_u32 s10, s8, 0x200
	s_addc_u32 s11, s9, 0
	global_load_dwordx4 v[88:91], v117, s[10:11]
	s_lshl_b32 s2, s29, 18
	s_add_u32 s10, s96, 0x1b200000
	s_addc_u32 s11, s97, 0
	s_add_u32 s10, s10, s2
	s_addc_u32 s11, s11, 0
	global_load_dwordx4 v[92:95], v118, s[10:11]
	s_add_i32 s12, s32, -8
	s_max_i32 s12, s12, 0
	s_mul_i32 s13, s12, 0x18000
	s_add_u32 s10, s8, 0x400
	s_addc_u32 s11, s9, 0
	s_add_u32 s10, s10, s13
	s_addc_u32 s11, s11, 0
	global_load_dwordx4 v[192:195], v117, s[10:11]
	s_lshl_b32 s13, s12, 7
	s_add_u32 s10, s96, 0x1ba00000
	s_addc_u32 s11, s97, 0
	s_add_u32 s10, s10, s2
	s_addc_u32 s11, s11, 0
	s_add_u32 s10, s10, s13
	s_addc_u32 s11, s11, 0
	global_load_dwordx4 v[196:199], v118, s[10:11]
	s_waitcnt vmcnt(30)
	s_nop 0
	v_or_b32_dpp v243, v243, v243 quad_perm:[1,0,3,2] row_mask:0xf bank_mask:0xf bound_ctrl:1
	s_nop 1
	v_or_b32_dpp v243, v243, v243 quad_perm:[2,3,0,1] row_mask:0xf bank_mask:0xf bound_ctrl:1
	s_nop 1
	v_or_b32_dpp v243, v243, v243 row_ror:4 row_mask:0xf bank_mask:0xf bound_ctrl:1
	s_nop 1
	v_or_b32_dpp v243, v243, v243 row_ror:8 row_mask:0xf bank_mask:0xf bound_ctrl:1
	v_mov_b32_e32 v242, v243
	s_nop 1
	v_permlane16_swap_b32_e32 v243, v242
	v_or_b32_e32 v243, v243, v242
	v_mov_b32_e32 v242, v243
	s_nop 1
	v_permlane32_swap_b32_e32 v243, v242
	v_or_b32_e32 v243, v243, v242
	s_nop 0
	v_readfirstlane_b32 s39, v243
	s_add_u32 s46, s8, 0x200
	s_addc_u32 s47, s9, 0
	s_lshl_b32 s2, s29, 18
	s_add_u32 s48, s96, 0x1b200000
	s_addc_u32 s49, s97, 0
	s_add_u32 s48, s48, s2
	s_addc_u32 s49, s49, 0
	s_lshl_b32 s2, 2, s32
	s_add_i32 s2, s2, -1
	s_and_b32 s38, s39, s2
	s_ff1_i32_b32 s15, s38
	s_add_i32 s65, s38, -1
	s_and_b32 s38, s38, s65
	s_ff1_i32_b32 s41, s38
	s_add_i32 s65, s38, -1
	s_and_b32 s38, s38, s65
	s_ff1_i32_b32 s42, s38
	s_add_i32 s65, s38, -1
	s_and_b32 s38, s38, s65
	s_cmp_eq_u32 s15, 0
	s_cbranch_scc1 .Lnsa_e0_1
	s_mov_b32 s40, s15
	s_max_i32 s65, s40, 0
	s_mul_i32 s56, s65, 0x18000
	s_lshl_b32 s58, s65, 7
	s_add_u32 s56, s46, s56
	s_addc_u32 s57, s47, 0
	s_add_u32 s58, s48, s58
	s_addc_u32 s59, s49, 0
	global_load_dwordx4 v[88:91], v117, s[56:57]
	global_load_dwordx4 v[92:95], v118, s[58:59]
.Lnsa_e0_1:
	s_max_i32 s65, s41, 0
	s_mul_i32 s56, s65, 0x18000
	s_lshl_b32 s58, s65, 7
	s_add_u32 s56, s46, s56
	s_addc_u32 s57, s47, 0
	s_add_u32 s58, s48, s58
	s_addc_u32 s59, s49, 0
	global_load_dwordx4 v[96:99], v117, s[56:57]
	global_load_dwordx4 v[100:103], v118, s[58:59]
	s_max_i32 s65, s42, 0
	s_mul_i32 s56, s65, 0x18000
	s_lshl_b32 s58, s65, 7
	s_add_u32 s56, s46, s56
	s_addc_u32 s57, s47, 0
	s_add_u32 s58, s48, s58
	s_addc_u32 s59, s49, 0
	global_load_dwordx4 v[104:107], v117, s[56:57]
	global_load_dwordx4 v[108:111], v118, s[58:59]
	s_waitcnt vmcnt(4)
	s_mov_b32 s7, 0x3e38aa3b
	v_lshlrev_b32_e32 v220, 16, v160
	v_lshlrev_b32_e32 v221, 16, v164
	v_mul_f32_e32 v222, v221, v125
	v_fma_f32 v222, v220, v124, -v222
	v_mul_f32_e32 v223, v220, v125
	v_fma_f32 v223, v221, v124, v223
	v_mul_f32_e32 v240, s7, v222
	v_mul_f32_e32 v244, s7, v223
	v_and_b32_e32 v220, 0xffff0000, v160
	v_and_b32_e32 v221, 0xffff0000, v164
	v_mul_f32_e32 v222, v221, v127
	v_fma_f32 v222, v220, v126, -v222
	v_mul_f32_e32 v223, v220, v127
	v_fma_f32 v223, v221, v126, v223
	v_mul_f32_e32 v241, s7, v222
	v_mul_f32_e32 v245, s7, v223
	v_lshlrev_b32_e32 v220, 16, v161
	v_lshlrev_b32_e32 v221, 16, v165
	v_mul_f32_e32 v222, v221, v129
	v_fma_f32 v222, v220, v128, -v222
	v_mul_f32_e32 v223, v220, v129
	v_fma_f32 v223, v221, v128, v223
	v_mul_f32_e32 v242, s7, v222
	v_mul_f32_e32 v246, s7, v223
	v_and_b32_e32 v220, 0xffff0000, v161
	v_and_b32_e32 v221, 0xffff0000, v165
	v_mul_f32_e32 v222, v221, v131
	v_fma_f32 v222, v220, v130, -v222
	v_mul_f32_e32 v223, v220, v131
	v_fma_f32 v223, v221, v130, v223
	v_mul_f32_e32 v243, s7, v222
	v_mul_f32_e32 v247, s7, v223
	v_cvt_pk_bf16_f32 v0, v240, v241
	v_cvt_pk_bf16_f32 v1, v242, v243
	v_cvt_pk_bf16_f32 v4, v244, v245
	v_cvt_pk_bf16_f32 v5, v246, v247
	v_lshlrev_b32_e32 v220, 16, v162
	v_lshlrev_b32_e32 v221, 16, v166
	v_mul_f32_e32 v222, v221, v133
	v_fma_f32 v222, v220, v132, -v222
	v_mul_f32_e32 v223, v220, v133
	v_fma_f32 v223, v221, v132, v223
	v_mul_f32_e32 v240, s7, v222
	v_mul_f32_e32 v244, s7, v223
	v_and_b32_e32 v220, 0xffff0000, v162
	v_and_b32_e32 v221, 0xffff0000, v166
	v_mul_f32_e32 v222, v221, v135
	v_fma_f32 v222, v220, v134, -v222
	v_mul_f32_e32 v223, v220, v135
	v_fma_f32 v223, v221, v134, v223
	v_mul_f32_e32 v241, s7, v222
	v_mul_f32_e32 v245, s7, v223
	v_lshlrev_b32_e32 v220, 16, v163
	v_lshlrev_b32_e32 v221, 16, v167
	v_mul_f32_e32 v222, v221, v137
	v_fma_f32 v222, v220, v136, -v222
	v_mul_f32_e32 v223, v220, v137
	v_fma_f32 v223, v221, v136, v223
	v_mul_f32_e32 v242, s7, v222
	v_mul_f32_e32 v246, s7, v223
	v_and_b32_e32 v220, 0xffff0000, v163
	v_and_b32_e32 v221, 0xffff0000, v167
	v_mul_f32_e32 v222, v221, v139
	v_fma_f32 v222, v220, v138, -v222
	v_mul_f32_e32 v223, v220, v139
	v_fma_f32 v223, v221, v138, v223
	v_mul_f32_e32 v243, s7, v222
	v_mul_f32_e32 v247, s7, v223
	v_cvt_pk_bf16_f32 v2, v240, v241
	v_cvt_pk_bf16_f32 v3, v242, v243
	v_cvt_pk_bf16_f32 v6, v244, v245
	v_cvt_pk_bf16_f32 v7, v246, v247
	v_lshlrev_b32_e32 v220, 16, v168
	v_lshlrev_b32_e32 v221, 16, v172
	v_mul_f32_e32 v222, v221, v141
	v_fma_f32 v222, v220, v140, -v222
	v_mul_f32_e32 v223, v220, v141
	v_fma_f32 v223, v221, v140, v223
	v_mul_f32_e32 v240, s7, v222
	v_mul_f32_e32 v244, s7, v223
	v_and_b32_e32 v220, 0xffff0000, v168
	v_and_b32_e32 v221, 0xffff0000, v172
	v_mul_f32_e32 v222, v221, v143
	v_fma_f32 v222, v220, v142, -v222
	v_mul_f32_e32 v223, v220, v143
	v_fma_f32 v223, v221, v142, v223
	v_mul_f32_e32 v241, s7, v222
	v_mul_f32_e32 v245, s7, v223
	v_lshlrev_b32_e32 v220, 16, v169
	v_lshlrev_b32_e32 v221, 16, v173
	v_mul_f32_e32 v222, v221, v145
	v_fma_f32 v222, v220, v144, -v222
	v_mul_f32_e32 v223, v220, v145
	v_fma_f32 v223, v221, v144, v223
	v_mul_f32_e32 v242, s7, v222
	v_mul_f32_e32 v246, s7, v223
	v_and_b32_e32 v220, 0xffff0000, v169
	v_and_b32_e32 v221, 0xffff0000, v173
	v_mul_f32_e32 v222, v221, v147
	v_fma_f32 v222, v220, v146, -v222
	v_mul_f32_e32 v223, v220, v147
	v_fma_f32 v223, v221, v146, v223
	v_mul_f32_e32 v243, s7, v222
	v_mul_f32_e32 v247, s7, v223
	v_cvt_pk_bf16_f32 v8, v240, v241
	v_cvt_pk_bf16_f32 v9, v242, v243
	v_cvt_pk_bf16_f32 v12, v244, v245
	v_cvt_pk_bf16_f32 v13, v246, v247
	v_lshlrev_b32_e32 v220, 16, v170
	v_lshlrev_b32_e32 v221, 16, v174
	v_mul_f32_e32 v222, v221, v149
	v_fma_f32 v222, v220, v148, -v222
	v_mul_f32_e32 v223, v220, v149
	v_fma_f32 v223, v221, v148, v223
	v_mul_f32_e32 v240, s7, v222
	v_mul_f32_e32 v244, s7, v223
	v_and_b32_e32 v220, 0xffff0000, v170
	v_and_b32_e32 v221, 0xffff0000, v174
	v_mul_f32_e32 v222, v221, v151
	v_fma_f32 v222, v220, v150, -v222
	v_mul_f32_e32 v223, v220, v151
	v_fma_f32 v223, v221, v150, v223
	v_mul_f32_e32 v241, s7, v222
	v_mul_f32_e32 v245, s7, v223
	v_lshlrev_b32_e32 v220, 16, v171
	v_lshlrev_b32_e32 v221, 16, v175
	v_mul_f32_e32 v222, v221, v155
	v_fma_f32 v222, v220, v154, -v222
	v_mul_f32_e32 v223, v220, v155
	v_fma_f32 v223, v221, v154, v223
	v_mul_f32_e32 v242, s7, v222
	v_mul_f32_e32 v246, s7, v223
	v_and_b32_e32 v220, 0xffff0000, v171
	v_and_b32_e32 v221, 0xffff0000, v175
	v_mul_f32_e32 v222, v221, v157
	v_fma_f32 v222, v220, v156, -v222
	v_mul_f32_e32 v223, v220, v157
	v_fma_f32 v223, v221, v156, v223
	v_mul_f32_e32 v243, s7, v222
	v_mul_f32_e32 v247, s7, v223
	v_cvt_pk_bf16_f32 v10, v240, v241
	v_cvt_pk_bf16_f32 v11, v242, v243
	v_cvt_pk_bf16_f32 v14, v244, v245
	v_cvt_pk_bf16_f32 v15, v246, v247
	v_and_b32_e32 v19, 0xffff0000, v17
	v_lshlrev_b32_e32 v18, 16, v17
	v_and_b32_e32 v17, 0xffff0000, v16
	v_lshlrev_b32_e32 v16, 16, v16
	v_and_b32_e32 v23, 0xffff0000, v21
	v_lshlrev_b32_e32 v22, 16, v21
	v_and_b32_e32 v21, 0xffff0000, v20
	v_lshlrev_b32_e32 v20, 16, v20
	v_and_b32_e32 v27, 0xffff0000, v25
	v_lshlrev_b32_e32 v26, 16, v25
	v_and_b32_e32 v25, 0xffff0000, v24
	v_lshlrev_b32_e32 v24, 16, v24
	v_and_b32_e32 v31, 0xffff0000, v29
	v_lshlrev_b32_e32 v30, 16, v29
	v_and_b32_e32 v29, 0xffff0000, v28
	v_lshlrev_b32_e32 v28, 16, v28
	v_and_b32_e32 v35, 0xffff0000, v33
	v_lshlrev_b32_e32 v34, 16, v33
	v_and_b32_e32 v33, 0xffff0000, v32
	v_lshlrev_b32_e32 v32, 16, v32
	v_and_b32_e32 v39, 0xffff0000, v37
	v_lshlrev_b32_e32 v38, 16, v37
	v_and_b32_e32 v37, 0xffff0000, v36
	v_lshlrev_b32_e32 v36, 16, v36
	v_and_b32_e32 v43, 0xffff0000, v41
	v_lshlrev_b32_e32 v42, 16, v41
	v_and_b32_e32 v41, 0xffff0000, v40
	v_lshlrev_b32_e32 v40, 16, v40
	v_and_b32_e32 v47, 0xffff0000, v45
	v_lshlrev_b32_e32 v46, 16, v45
	v_and_b32_e32 v45, 0xffff0000, v44
	v_lshlrev_b32_e32 v44, 16, v44
	ds_write_b128 v250, v[16:19] offset:0
	ds_write_b128 v250, v[20:23] offset:1024
	ds_write_b128 v250, v[24:27] offset:2048
	ds_write_b128 v250, v[28:31] offset:3072
	ds_write_b128 v250, v[32:35] offset:4096
	ds_write_b128 v250, v[36:39] offset:5120
	ds_write_b128 v250, v[40:43] offset:6144
	ds_write_b128 v250, v[44:47] offset:7168
	s_waitcnt lgkmcnt(0)
	s_mov_b32 s37, 0
.Lnsa_br:
	s_mul_i32 s2, s30, 0x300000
	s_add_u32 s46, s96, 0x10000000
	s_addc_u32 s47, s97, 0
	s_add_u32 s46, s46, s2
	s_addc_u32 s47, s47, 0
	s_lshl_b32 s2, s31, 7
	s_cmp_eq_u32 s37, 1
	s_mov_b32 s3, 0x200
	s_cselect_b32 s3, 0x400, s3
	s_add_i32 s2, s2, s3
	s_add_u32 s46, s46, s2
	s_addc_u32 s47, s47, 0
	s_cmp_eq_u32 s37, 1
	s_mov_b32 s3, 0x1b200000
	s_cselect_b32 s3, 0x1ba00000, s3
	s_add_u32 s48, s96, s3
	s_addc_u32 s49, s97, 0
	s_lshl_b32 s2, s29, 18
	s_add_u32 s48, s48, s2
	s_addc_u32 s49, s49, 0
	s_cmp_eq_u32 s37, 1
	s_mov_b32 s45, 0x7fffffff
	s_cselect_b32 s45, 0x200, s45
	s_add_i32 s14, s32, -8
	s_cmp_eq_u32 s37, 1
	s_cselect_b32 s14, s14, -2
	s_cselect_b64 vcc, -1, 0
	v_mov_b32_e32 v220, -1
	s_nop 1
	v_cndmask_b32_e32 v248, v84, v220, vcc
	v_cndmask_b32_e32 v249, v85, v220, vcc
	v_mov_b32_e32 v80, 0
	v_mov_b32_e32 v200, 0xefa18f08
	v_mov_b32_e32 v82, 0
	v_mov_b32_e32 v48, 0
	v_mov_b32_e32 v49, 0
	v_mov_b32_e32 v50, 0
	v_mov_b32_e32 v51, 0
	v_mov_b32_e32 v52, 0
	v_mov_b32_e32 v53, 0
	v_mov_b32_e32 v54, 0
	v_mov_b32_e32 v55, 0
	v_mov_b32_e32 v56, 0
	v_mov_b32_e32 v57, 0
	v_mov_b32_e32 v58, 0
	v_mov_b32_e32 v59, 0
	v_mov_b32_e32 v60, 0
	v_mov_b32_e32 v61, 0
	v_mov_b32_e32 v62, 0
	v_mov_b32_e32 v63, 0
	v_mov_b32_e32 v81, 0
	v_mov_b32_e32 v201, 0xefa18f08
	v_mov_b32_e32 v83, 0
	v_mov_b32_e32 v64, 0
	v_mov_b32_e32 v65, 0
	v_mov_b32_e32 v66, 0
	v_mov_b32_e32 v67, 0
	v_mov_b32_e32 v68, 0
	v_mov_b32_e32 v69, 0
	v_mov_b32_e32 v70, 0
	v_mov_b32_e32 v71, 0
	v_mov_b32_e32 v72, 0
	v_mov_b32_e32 v73, 0
	v_mov_b32_e32 v74, 0
	v_mov_b32_e32 v75, 0
	v_mov_b32_e32 v76, 0
	v_mov_b32_e32 v77, 0
	v_mov_b32_e32 v78, 0
	v_mov_b32_e32 v79, 0
	v_mov_b32_e32 v212, 0
	v_mov_b32_e32 v213, 0
	v_mov_b32_e32 v214, 0
	v_mov_b32_e32 v215, 0
	v_mov_b32_e32 v216, 0
	v_mov_b32_e32 v217, 0
	v_mov_b32_e32 v218, 0
	v_mov_b32_e32 v219, 0
	s_cmp_eq_u32 s37, 0
	s_cbranch_scc1 .Lnsa_ready_2
	s_lshl_b32 s2, 2, s32
	s_add_i32 s38, s2, -1
	s_cmp_lt_u32 s32, 8
	s_cbranch_scc1 .Lnsa_ready_2_w
	s_add_i32 s3, s32, -8
	s_lshl_b32 s38, 0x1ff, s3
.Lnsa_ready_2_w:
	s_ff1_i32_b32 s15, s38
	s_add_i32 s65, s38, -1
	s_and_b32 s38, s38, s65
	s_ff1_i32_b32 s41, s38
	s_add_i32 s65, s38, -1
	s_and_b32 s38, s38, s65
	s_ff1_i32_b32 s42, s38
	s_add_i32 s65, s38, -1
	s_and_b32 s38, s38, s65
	s_max_i32 s65, s41, 0
	s_mul_i32 s56, s65, 0x18000
	s_lshl_b32 s58, s65, 7
	s_add_u32 s56, s46, s56
	s_addc_u32 s57, s47, 0
	s_add_u32 s58, s48, s58
	s_addc_u32 s59, s49, 0
	global_load_dwordx4 v[96:99], v117, s[56:57]
	global_load_dwordx4 v[100:103], v118, s[58:59]
	s_max_i32 s65, s42, 0
	s_mul_i32 s56, s65, 0x18000
	s_lshl_b32 s58, s65, 7
	s_add_u32 s56, s46, s56
	s_addc_u32 s57, s47, 0
	s_add_u32 s58, s48, s58
	s_addc_u32 s59, s49, 0
	global_load_dwordx4 v[104:107], v117, s[56:57]
	global_load_dwordx4 v[108:111], v118, s[58:59]
	s_waitcnt vmcnt(4)
	v_add_u32_e32 v244, s50, v114
	v_add_u32_e32 v245, s50, v123
	ds_write_b128 v244, v[192:195]
	ds_write_b128 v245, v[196:199]
	s_branch .Lnsa_ready_2_x
.Lnsa_ready_2:
	s_waitcnt vmcnt(4)
	v_add_u32_e32 v244, s50, v114
	v_add_u32_e32 v245, s50, v123
	ds_write_b128 v244, v[88:91]
	ds_write_b128 v245, v[92:95]
.Lnsa_ready_2_x:
	s_ff1_i32_b32 s40, s38
	s_add_i32 s65, s38, -1
	s_and_b32 s38, s38, s65
	s_max_i32 s65, s40, 0
	s_mul_i32 s56, s65, 0x18000
	s_lshl_b32 s58, s65, 7
	s_add_u32 s56, s46, s56
	s_addc_u32 s57, s47, 0
	s_add_u32 s58, s48, s58
	s_addc_u32 s59, s49, 0
	global_load_dwordx4 v[88:91], v117, s[56:57]
	global_load_dwordx4 v[92:95], v118, s[58:59]
	s_waitcnt lgkmcnt(0)
	s_barrier
	v_add_u32_e32 v225, s50, v115
	v_add_u32_e32 v246, s50, v122
	ds_read_b128 v[160:163], v225 offset:0
	ds_read_b128 v[168:171], v225 offset:2048
	ds_read_b128 v[176:179], v225 offset:4096
	ds_read_b128 v[184:187], v225 offset:6144
	ds_read_b128 v[164:167], v246 offset:0
	ds_read_b128 v[172:175], v246 offset:2048
	ds_read_b128 v[180:183], v246 offset:4096
	ds_read_b128 v[188:191], v246 offset:6144
.Lnsa_loop_3:
	s_cmp_lt_i32 s15, 0
	s_cbranch_scc1 .Lnsa_brk_4
	s_waitcnt lgkmcnt(0)
	v_mfma_f32_16x16x32_bf16 v[64:67], v[16:19], v[212:215], v[64:67]
	s_lshl_b32 s44, s15, 6
	s_lshl_b32 s65, 1, s15
	v_and_b32_e32 v220, s65, v248
	v_mfma_f32_16x16x32_bf16 v[68:71], v[24:27], v[212:215], v[68:71]
	v_and_b32_e32 v221, s65, v249
	v_cmp_ne_u32_e64 s[60:61], 0, v220
	v_cmp_ne_u32_e64 s[62:63], 0, v221
	v_mfma_f32_16x16x32_bf16 v[72:75], v[32:35], v[212:215], v[72:75]
	s_cmp_eq_u32 s15, s32
	s_cselect_b32 s64, 1, 0
	s_cmp_eq_u32 s15, s14
	v_mfma_f32_16x16x32_bf16 v[76:79], v[40:43], v[212:215], v[76:79]
	s_cselect_b32 s64, 1, s64
	s_xor_b32 s17, s50, 0x4800
	v_add_u32_e32 v244, s17, v114
	v_mfma_f32_16x16x32_bf16 v[64:67], v[20:23], v[216:219], v[64:67]
	v_add_u32_e32 v245, s17, v123
	v_add_u32_e32 v247, s50, v116
	v_cndmask_b32_e64 v228, v227, v80, s[60:61]
	v_mfma_f32_16x16x32_bf16 v[68:71], v[28:31], v[216:219], v[68:71]
	v_cndmask_b32_e64 v229, v227, v80, s[60:61]
	v_cndmask_b32_e64 v230, v227, v80, s[60:61]
	v_cndmask_b32_e64 v231, v227, v80, s[60:61]
	v_mfma_f32_16x16x32_bf16 v[72:75], v[36:39], v[216:219], v[72:75]
	v_cndmask_b32_e64 v236, v227, v81, s[62:63]
	v_cndmask_b32_e64 v237, v227, v81, s[62:63]
	v_cndmask_b32_e64 v238, v227, v81, s[62:63]
	v_mfma_f32_16x16x32_bf16 v[76:79], v[44:47], v[216:219], v[76:79]
	v_cndmask_b32_e64 v239, v227, v81, s[62:63]
	ds_read_b64 v[16:17], v247 offset:9216
	ds_read_b64 v[18:19], v247 offset:9248
	ds_read_b64 v[20:21], v247 offset:9280
	ds_read_b64 v[22:23], v247 offset:9312
	ds_read_b64 v[24:25], v247 offset:11520
	ds_read_b64 v[26:27], v247 offset:11552
	ds_read_b64 v[28:29], v247 offset:11584
	ds_read_b64 v[30:31], v247 offset:11616
	ds_read_b64 v[32:33], v247 offset:13824
	ds_read_b64 v[34:35], v247 offset:13856
	ds_read_b64 v[36:37], v247 offset:13888
	ds_read_b64 v[38:39], v247 offset:13920
	ds_read_b64 v[40:41], v247 offset:16128
	ds_read_b64 v[42:43], v247 offset:16160
	ds_read_b64 v[44:45], v247 offset:16192
	ds_read_b64 v[46:47], v247 offset:16224
	v_mfma_f32_16x16x32_bf16 v[124:127], v[160:163], v[0:3], v[228:231]
	s_waitcnt vmcnt(4)
	ds_write_b128 v244, v[96:99]
	v_mfma_f32_16x16x32_bf16 v[128:131], v[168:171], v[0:3], v[228:231]
	ds_write_b128 v245, v[100:103]
	s_mov_b32 s16, s41
	v_mfma_f32_16x16x32_bf16 v[132:135], v[176:179], v[0:3], v[228:231]
	s_ff1_i32_b32 s41, s38
	s_add_i32 s65, s38, -1
	v_mfma_f32_16x16x32_bf16 v[136:139], v[184:187], v[0:3], v[228:231]
	s_and_b32 s38, s38, s65
	s_max_i32 s65, s41, 0
	v_mfma_f32_16x16x32_bf16 v[124:127], v[164:167], v[4:7], v[124:127]
	s_mul_i32 s56, s65, 0x18000
	s_lshl_b32 s58, s65, 7
	v_mfma_f32_16x16x32_bf16 v[128:131], v[172:175], v[4:7], v[128:131]
	s_add_u32 s56, s46, s56
	s_addc_u32 s57, s47, 0
	v_mfma_f32_16x16x32_bf16 v[132:135], v[180:183], v[4:7], v[132:135]
	s_add_u32 s58, s48, s58
	s_addc_u32 s59, s49, 0
	v_mfma_f32_16x16x32_bf16 v[136:139], v[188:191], v[4:7], v[136:139]
	global_load_dwordx4 v[96:99], v117, s[56:57]
	global_load_dwordx4 v[100:103], v118, s[58:59]
	s_cmp_eq_u32 s64, 0
	s_cbranch_scc1 .Lnsa_nm_5
	v_lshl_add_u32 v222, v113, 2, s44
	v_sub_u32_e32 v120, v86, v222
	v_cndmask_b32_e64 v240, -1, v120, s[60:61]
	v_subrev_u32_e32 v220, 0, v240
	v_subrev_u32_e32 v221, 1, v240
	v_subrev_u32_e32 v222, 2, v240
	v_subrev_u32_e32 v223, 3, v240
	v_cmp_gt_u32_e64 s[52:53], s45, v220
	v_cmp_gt_u32_e64 s[54:55], s45, v221
	v_cmp_gt_u32_e64 s[56:57], s45, v222
	v_cmp_gt_u32_e64 s[58:59], s45, v223
	v_cndmask_b32_e64 v124, v224, v124, s[52:53]
	v_cndmask_b32_e64 v125, v224, v125, s[54:55]
	v_cndmask_b32_e64 v126, v224, v126, s[56:57]
	v_cndmask_b32_e64 v127, v224, v127, s[58:59]
	v_subrev_u32_e32 v220, 16, v240
	v_subrev_u32_e32 v221, 17, v240
	v_subrev_u32_e32 v222, 18, v240
	v_subrev_u32_e32 v223, 19, v240
	v_cmp_gt_u32_e64 s[52:53], s45, v220
	v_cmp_gt_u32_e64 s[54:55], s45, v221
	v_cmp_gt_u32_e64 s[56:57], s45, v222
	v_cmp_gt_u32_e64 s[58:59], s45, v223
	v_cndmask_b32_e64 v128, v224, v128, s[52:53]
	v_cndmask_b32_e64 v129, v224, v129, s[54:55]
	v_cndmask_b32_e64 v130, v224, v130, s[56:57]
	v_cndmask_b32_e64 v131, v224, v131, s[58:59]
	v_subrev_u32_e32 v220, 32, v240
	v_subrev_u32_e32 v221, 33, v240
	v_subrev_u32_e32 v222, 34, v240
	v_subrev_u32_e32 v223, 35, v240
	v_cmp_gt_u32_e64 s[52:53], s45, v220
	v_cmp_gt_u32_e64 s[54:55], s45, v221
	v_cmp_gt_u32_e64 s[56:57], s45, v222
	v_cmp_gt_u32_e64 s[58:59], s45, v223
	v_cndmask_b32_e64 v132, v224, v132, s[52:53]
	v_cndmask_b32_e64 v133, v224, v133, s[54:55]
	v_cndmask_b32_e64 v134, v224, v134, s[56:57]
	v_cndmask_b32_e64 v135, v224, v135, s[58:59]
	v_subrev_u32_e32 v220, 48, v240
	v_subrev_u32_e32 v221, 49, v240
	v_subrev_u32_e32 v222, 50, v240
	v_subrev_u32_e32 v223, 51, v240
	v_cmp_gt_u32_e64 s[52:53], s45, v220
	v_cmp_gt_u32_e64 s[54:55], s45, v221
	v_cmp_gt_u32_e64 s[56:57], s45, v222
	v_cmp_gt_u32_e64 s[58:59], s45, v223
	v_cndmask_b32_e64 v136, v224, v136, s[52:53]
	v_cndmask_b32_e64 v137, v224, v137, s[54:55]
	v_cndmask_b32_e64 v138, v224, v138, s[56:57]
	v_cndmask_b32_e64 v139, v224, v139, s[58:59]

.Lnsa_rb_7:
	v_exp_f32_e32 v124, v124
	v_mfma_f32_16x16x32_bf16 v[140:143], v[164:167], v[12:15], v[140:143]
	v_exp_f32_e32 v125, v125
	v_exp_f32_e32 v126, v126
	v_exp_f32_e32 v127, v127
	v_mfma_f32_16x16x32_bf16 v[144:147], v[172:175], v[12:15], v[144:147]
	v_exp_f32_e32 v128, v128
	v_exp_f32_e32 v129, v129
	v_exp_f32_e32 v130, v130
	v_mfma_f32_16x16x32_bf16 v[148:151], v[180:183], v[12:15], v[148:151]
	v_exp_f32_e32 v131, v131
	v_exp_f32_e32 v132, v132
	v_exp_f32_e32 v133, v133
	v_mfma_f32_16x16x32_bf16 v[154:157], v[188:191], v[12:15], v[154:157]
	v_exp_f32_e32 v134, v134
	v_exp_f32_e32 v135, v135
	v_exp_f32_e32 v136, v136
	v_exp_f32_e32 v137, v137
	v_exp_f32_e32 v138, v138
	v_exp_f32_e32 v139, v139
	v_add_f32_e32 v232, v124, v125
	v_add_f32_e32 v232, v232, v126
	v_add_f32_e32 v232, v232, v127
	v_add_f32_e32 v232, v232, v128
	v_add_f32_e32 v232, v232, v129
	v_add_f32_e32 v232, v232, v130
	v_add_f32_e32 v232, v232, v131
	v_add_f32_e32 v232, v232, v132
	v_add_f32_e32 v232, v232, v133
	v_add_f32_e32 v232, v232, v134
	v_add_f32_e32 v232, v232, v135
	v_add_f32_e32 v232, v232, v136
	v_add_f32_e32 v232, v232, v137
	v_add_f32_e32 v232, v232, v138
	v_add_f32_e32 v232, v232, v139
	v_add_f32_e32 v82, v82, v232
	v_cvt_pk_bf16_f32 v204, v124, v125
	v_cvt_pk_bf16_f32 v205, v126, v127
	v_cvt_pk_bf16_f32 v206, v128, v129
	v_cvt_pk_bf16_f32 v207, v130, v131
	v_cvt_pk_bf16_f32 v208, v132, v133
	v_cvt_pk_bf16_f32 v209, v134, v135
	v_cvt_pk_bf16_f32 v210, v136, v137
	v_cvt_pk_bf16_f32 v211, v138, v139
	s_cmp_eq_u32 s64, 0
	s_cbranch_scc1 .Lnsa_nm_10
	v_lshl_add_u32 v222, v113, 2, s44
	v_sub_u32_e32 v121, v87, v222
	v_cndmask_b32_e64 v240, -1, v121, s[62:63]
	v_subrev_u32_e32 v220, 0, v240
	v_subrev_u32_e32 v221, 1, v240
	v_subrev_u32_e32 v222, 2, v240
	v_subrev_u32_e32 v223, 3, v240
	v_cmp_gt_u32_e64 s[52:53], s45, v220
	v_cmp_gt_u32_e64 s[54:55], s45, v221
	v_cmp_gt_u32_e64 s[56:57], s45, v222
	v_cmp_gt_u32_e64 s[58:59], s45, v223
	v_cndmask_b32_e64 v140, v224, v140, s[52:53]
	v_cndmask_b32_e64 v141, v224, v141, s[54:55]
	v_cndmask_b32_e64 v142, v224, v142, s[56:57]
	v_cndmask_b32_e64 v143, v224, v143, s[58:59]
	v_subrev_u32_e32 v220, 16, v240
	v_subrev_u32_e32 v221, 17, v240
	v_subrev_u32_e32 v222, 18, v240
	v_subrev_u32_e32 v223, 19, v240
	v_cmp_gt_u32_e64 s[52:53], s45, v220
	v_cmp_gt_u32_e64 s[54:55], s45, v221
	v_cmp_gt_u32_e64 s[56:57], s45, v222
	v_cmp_gt_u32_e64 s[58:59], s45, v223
	v_cndmask_b32_e64 v144, v224, v144, s[52:53]
	v_cndmask_b32_e64 v145, v224, v145, s[54:55]
	v_cndmask_b32_e64 v146, v224, v146, s[56:57]
	v_cndmask_b32_e64 v147, v224, v147, s[58:59]
	v_subrev_u32_e32 v220, 32, v240
	v_subrev_u32_e32 v221, 33, v240
	v_subrev_u32_e32 v222, 34, v240
	v_subrev_u32_e32 v223, 35, v240
	v_cmp_gt_u32_e64 s[52:53], s45, v220
	v_cmp_gt_u32_e64 s[54:55], s45, v221
	v_cmp_gt_u32_e64 s[56:57], s45, v222
	v_cmp_gt_u32_e64 s[58:59], s45, v223
	v_cndmask_b32_e64 v148, v224, v148, s[52:53]
	v_cndmask_b32_e64 v149, v224, v149, s[54:55]
	v_cndmask_b32_e64 v150, v224, v150, s[56:57]
	v_cndmask_b32_e64 v151, v224, v151, s[58:59]
	v_subrev_u32_e32 v220, 48, v240
	v_subrev_u32_e32 v221, 49, v240
	v_subrev_u32_e32 v222, 50, v240
	v_subrev_u32_e32 v223, 51, v240
	v_cmp_gt_u32_e64 s[52:53], s45, v220
	v_cmp_gt_u32_e64 s[54:55], s45, v221
	v_cmp_gt_u32_e64 s[56:57], s45, v222
	v_cmp_gt_u32_e64 s[58:59], s45, v223
	v_cndmask_b32_e64 v154, v224, v154, s[52:53]
	v_cndmask_b32_e64 v155, v224, v155, s[54:55]
	v_cndmask_b32_e64 v156, v224, v156, s[56:57]
	v_cndmask_b32_e64 v157, v224, v157, s[58:59]

.Lnsa_rb_9:
	s_waitcnt lgkmcnt(0)
	s_barrier
	s_mov_b32 s50, s17
	s_mov_b32 s15, s16
	v_add_u32_e32 v225, s50, v115
	v_add_u32_e32 v246, s50, v122
	ds_read_b128 v[160:163], v225 offset:0
	ds_read_b128 v[168:171], v225 offset:2048
	ds_read_b128 v[176:179], v225 offset:4096
	ds_read_b128 v[184:187], v225 offset:6144
	ds_read_b128 v[164:167], v246 offset:0
	ds_read_b128 v[172:175], v246 offset:2048
	ds_read_b128 v[180:183], v246 offset:4096
	ds_read_b128 v[188:191], v246 offset:6144
	v_mfma_f32_16x16x32_bf16 v[48:51], v[16:19], v[204:207], v[48:51]
	v_exp_f32_e32 v140, v140
	v_exp_f32_e32 v141, v141
	v_exp_f32_e32 v142, v142
	v_exp_f32_e32 v143, v143
	v_mfma_f32_16x16x32_bf16 v[52:55], v[24:27], v[204:207], v[52:55]
	v_exp_f32_e32 v144, v144
	v_exp_f32_e32 v145, v145
	v_exp_f32_e32 v146, v146
	v_exp_f32_e32 v147, v147
	v_mfma_f32_16x16x32_bf16 v[56:59], v[32:35], v[204:207], v[56:59]
	v_exp_f32_e32 v148, v148
	v_exp_f32_e32 v149, v149
	v_exp_f32_e32 v150, v150
	v_exp_f32_e32 v151, v151
	v_mfma_f32_16x16x32_bf16 v[60:63], v[40:43], v[204:207], v[60:63]
	v_exp_f32_e32 v154, v154
	v_exp_f32_e32 v155, v155
	v_exp_f32_e32 v156, v156
	v_exp_f32_e32 v157, v157
	v_mfma_f32_16x16x32_bf16 v[48:51], v[20:23], v[208:211], v[48:51]
	v_add_f32_e32 v232, v140, v141
	v_add_f32_e32 v232, v232, v142
	v_add_f32_e32 v232, v232, v143
	v_add_f32_e32 v232, v232, v144
	v_mfma_f32_16x16x32_bf16 v[52:55], v[28:31], v[208:211], v[52:55]
	v_add_f32_e32 v232, v232, v145
	v_add_f32_e32 v232, v232, v146
	v_add_f32_e32 v232, v232, v147
	v_add_f32_e32 v232, v232, v148
	v_mfma_f32_16x16x32_bf16 v[56:59], v[36:39], v[208:211], v[56:59]
	v_add_f32_e32 v232, v232, v149
	v_add_f32_e32 v232, v232, v150
	v_add_f32_e32 v232, v232, v151
	v_add_f32_e32 v232, v232, v154
	v_mfma_f32_16x16x32_bf16 v[60:63], v[44:47], v[208:211], v[60:63]
	v_add_f32_e32 v232, v232, v155
	v_add_f32_e32 v232, v232, v156
	v_add_f32_e32 v232, v232, v157
	v_add_f32_e32 v83, v83, v232
	v_cvt_pk_bf16_f32 v212, v140, v141
	v_cvt_pk_bf16_f32 v213, v142, v143
	v_cvt_pk_bf16_f32 v214, v144, v145
	v_cvt_pk_bf16_f32 v215, v146, v147
	v_cvt_pk_bf16_f32 v216, v148, v149
	v_cvt_pk_bf16_f32 v217, v150, v151
	v_cvt_pk_bf16_f32 v218, v154, v155
	v_cvt_pk_bf16_f32 v219, v156, v157
	s_cmp_lt_i32 s15, 0
	s_cbranch_scc1 .Lnsa_brk_4
	s_waitcnt lgkmcnt(0)
	v_mfma_f32_16x16x32_bf16 v[64:67], v[16:19], v[212:215], v[64:67]
	s_lshl_b32 s44, s15, 6
	s_lshl_b32 s65, 1, s15
	v_and_b32_e32 v220, s65, v248
	v_mfma_f32_16x16x32_bf16 v[68:71], v[24:27], v[212:215], v[68:71]
	v_and_b32_e32 v221, s65, v249
	v_cmp_ne_u32_e64 s[60:61], 0, v220
	v_cmp_ne_u32_e64 s[62:63], 0, v221
	v_mfma_f32_16x16x32_bf16 v[72:75], v[32:35], v[212:215], v[72:75]
	s_cmp_eq_u32 s15, s32
	s_cselect_b32 s64, 1, 0
	s_cmp_eq_u32 s15, s14
	v_mfma_f32_16x16x32_bf16 v[76:79], v[40:43], v[212:215], v[76:79]
	s_cselect_b32 s64, 1, s64
	s_xor_b32 s17, s50, 0x4800
	v_add_u32_e32 v244, s17, v114
	v_mfma_f32_16x16x32_bf16 v[64:67], v[20:23], v[216:219], v[64:67]
	v_add_u32_e32 v245, s17, v123
	v_add_u32_e32 v247, s50, v116
	v_cndmask_b32_e64 v228, v227, v80, s[60:61]
	v_mfma_f32_16x16x32_bf16 v[68:71], v[28:31], v[216:219], v[68:71]
	v_cndmask_b32_e64 v229, v227, v80, s[60:61]
	v_cndmask_b32_e64 v230, v227, v80, s[60:61]
	v_cndmask_b32_e64 v231, v227, v80, s[60:61]
	v_mfma_f32_16x16x32_bf16 v[72:75], v[36:39], v[216:219], v[72:75]
	v_cndmask_b32_e64 v236, v227, v81, s[62:63]
	v_cndmask_b32_e64 v237, v227, v81, s[62:63]
	v_cndmask_b32_e64 v238, v227, v81, s[62:63]
	v_mfma_f32_16x16x32_bf16 v[76:79], v[44:47], v[216:219], v[76:79]
	v_cndmask_b32_e64 v239, v227, v81, s[62:63]
	ds_read_b64 v[16:17], v247 offset:9216
	ds_read_b64 v[18:19], v247 offset:9248
	ds_read_b64 v[20:21], v247 offset:9280
	ds_read_b64 v[22:23], v247 offset:9312
	ds_read_b64 v[24:25], v247 offset:11520
	ds_read_b64 v[26:27], v247 offset:11552
	ds_read_b64 v[28:29], v247 offset:11584
	ds_read_b64 v[30:31], v247 offset:11616
	ds_read_b64 v[32:33], v247 offset:13824
	ds_read_b64 v[34:35], v247 offset:13856
	ds_read_b64 v[36:37], v247 offset:13888
	ds_read_b64 v[38:39], v247 offset:13920
	ds_read_b64 v[40:41], v247 offset:16128
	ds_read_b64 v[42:43], v247 offset:16160
	ds_read_b64 v[44:45], v247 offset:16192
	ds_read_b64 v[46:47], v247 offset:16224
	v_mfma_f32_16x16x32_bf16 v[124:127], v[160:163], v[0:3], v[228:231]
	s_waitcnt vmcnt(4)
	ds_write_b128 v244, v[104:107]
	v_mfma_f32_16x16x32_bf16 v[128:131], v[168:171], v[0:3], v[228:231]
	ds_write_b128 v245, v[108:111]
	s_mov_b32 s16, s42
	v_mfma_f32_16x16x32_bf16 v[132:135], v[176:179], v[0:3], v[228:231]
	s_ff1_i32_b32 s42, s38
	s_add_i32 s65, s38, -1
	v_mfma_f32_16x16x32_bf16 v[136:139], v[184:187], v[0:3], v[228:231]
	s_and_b32 s38, s38, s65
	s_max_i32 s65, s42, 0
	v_mfma_f32_16x16x32_bf16 v[124:127], v[164:167], v[4:7], v[124:127]
	s_mul_i32 s56, s65, 0x18000
	s_lshl_b32 s58, s65, 7
	v_mfma_f32_16x16x32_bf16 v[128:131], v[172:175], v[4:7], v[128:131]
	s_add_u32 s56, s46, s56
	s_addc_u32 s57, s47, 0
	v_mfma_f32_16x16x32_bf16 v[132:135], v[180:183], v[4:7], v[132:135]
	s_add_u32 s58, s48, s58
	s_addc_u32 s59, s49, 0
	v_mfma_f32_16x16x32_bf16 v[136:139], v[188:191], v[4:7], v[136:139]
	global_load_dwordx4 v[104:107], v117, s[56:57]
	global_load_dwordx4 v[108:111], v118, s[58:59]
	s_cmp_eq_u32 s64, 0
	s_cbranch_scc1 .Lnsa_nm_11
	v_lshl_add_u32 v222, v113, 2, s44
	v_sub_u32_e32 v120, v86, v222
	v_cndmask_b32_e64 v240, -1, v120, s[60:61]
	v_subrev_u32_e32 v220, 0, v240
	v_subrev_u32_e32 v221, 1, v240
	v_subrev_u32_e32 v222, 2, v240
	v_subrev_u32_e32 v223, 3, v240
	v_cmp_gt_u32_e64 s[52:53], s45, v220
	v_cmp_gt_u32_e64 s[54:55], s45, v221
	v_cmp_gt_u32_e64 s[56:57], s45, v222
	v_cmp_gt_u32_e64 s[58:59], s45, v223
	v_cndmask_b32_e64 v124, v224, v124, s[52:53]
	v_cndmask_b32_e64 v125, v224, v125, s[54:55]
	v_cndmask_b32_e64 v126, v224, v126, s[56:57]
	v_cndmask_b32_e64 v127, v224, v127, s[58:59]
	v_subrev_u32_e32 v220, 16, v240
	v_subrev_u32_e32 v221, 17, v240
	v_subrev_u32_e32 v222, 18, v240
	v_subrev_u32_e32 v223, 19, v240
	v_cmp_gt_u32_e64 s[52:53], s45, v220
	v_cmp_gt_u32_e64 s[54:55], s45, v221
	v_cmp_gt_u32_e64 s[56:57], s45, v222
	v_cmp_gt_u32_e64 s[58:59], s45, v223
	v_cndmask_b32_e64 v128, v224, v128, s[52:53]
	v_cndmask_b32_e64 v129, v224, v129, s[54:55]
	v_cndmask_b32_e64 v130, v224, v130, s[56:57]
	v_cndmask_b32_e64 v131, v224, v131, s[58:59]
	v_subrev_u32_e32 v220, 32, v240
	v_subrev_u32_e32 v221, 33, v240
	v_subrev_u32_e32 v222, 34, v240
	v_subrev_u32_e32 v223, 35, v240
	v_cmp_gt_u32_e64 s[52:53], s45, v220
	v_cmp_gt_u32_e64 s[54:55], s45, v221
	v_cmp_gt_u32_e64 s[56:57], s45, v222
	v_cmp_gt_u32_e64 s[58:59], s45, v223
	v_cndmask_b32_e64 v132, v224, v132, s[52:53]
	v_cndmask_b32_e64 v133, v224, v133, s[54:55]
	v_cndmask_b32_e64 v134, v224, v134, s[56:57]
	v_cndmask_b32_e64 v135, v224, v135, s[58:59]
	v_subrev_u32_e32 v220, 48, v240
	v_subrev_u32_e32 v221, 49, v240
	v_subrev_u32_e32 v222, 50, v240
	v_subrev_u32_e32 v223, 51, v240
	v_cmp_gt_u32_e64 s[52:53], s45, v220
	v_cmp_gt_u32_e64 s[54:55], s45, v221
	v_cmp_gt_u32_e64 s[56:57], s45, v222
	v_cmp_gt_u32_e64 s[58:59], s45, v223
	v_cndmask_b32_e64 v136, v224, v136, s[52:53]
	v_cndmask_b32_e64 v137, v224, v137, s[54:55]
	v_cndmask_b32_e64 v138, v224, v138, s[56:57]
	v_cndmask_b32_e64 v139, v224, v139, s[58:59]

.Lnsa_rb_15:
	s_waitcnt lgkmcnt(0)
	s_barrier
	s_mov_b32 s50, s17
	s_mov_b32 s15, s16
	v_add_u32_e32 v225, s50, v115
	v_add_u32_e32 v246, s50, v122
	ds_read_b128 v[160:163], v225 offset:0
	ds_read_b128 v[168:171], v225 offset:2048
	ds_read_b128 v[176:179], v225 offset:4096
	ds_read_b128 v[184:187], v225 offset:6144
	ds_read_b128 v[164:167], v246 offset:0
	ds_read_b128 v[172:175], v246 offset:2048
	ds_read_b128 v[180:183], v246 offset:4096
	ds_read_b128 v[188:191], v246 offset:6144
	v_mfma_f32_16x16x32_bf16 v[48:51], v[16:19], v[204:207], v[48:51]
	v_exp_f32_e32 v140, v140
	v_exp_f32_e32 v141, v141
	v_exp_f32_e32 v142, v142
	v_exp_f32_e32 v143, v143
	v_mfma_f32_16x16x32_bf16 v[52:55], v[24:27], v[204:207], v[52:55]
	v_exp_f32_e32 v144, v144
	v_exp_f32_e32 v145, v145
	v_exp_f32_e32 v146, v146
	v_exp_f32_e32 v147, v147
	v_mfma_f32_16x16x32_bf16 v[56:59], v[32:35], v[204:207], v[56:59]
	v_exp_f32_e32 v148, v148
	v_exp_f32_e32 v149, v149
	v_exp_f32_e32 v150, v150
	v_exp_f32_e32 v151, v151
	v_mfma_f32_16x16x32_bf16 v[60:63], v[40:43], v[204:207], v[60:63]
	v_exp_f32_e32 v154, v154
	v_exp_f32_e32 v155, v155
	v_exp_f32_e32 v156, v156
	v_exp_f32_e32 v157, v157
	v_mfma_f32_16x16x32_bf16 v[48:51], v[20:23], v[208:211], v[48:51]
	v_add_f32_e32 v232, v140, v141
	v_add_f32_e32 v232, v232, v142
	v_add_f32_e32 v232, v232, v143
	v_add_f32_e32 v232, v232, v144
	v_mfma_f32_16x16x32_bf16 v[52:55], v[28:31], v[208:211], v[52:55]
	v_add_f32_e32 v232, v232, v145
	v_add_f32_e32 v232, v232, v146
	v_add_f32_e32 v232, v232, v147
	v_add_f32_e32 v232, v232, v148
	v_mfma_f32_16x16x32_bf16 v[56:59], v[36:39], v[208:211], v[56:59]
	v_add_f32_e32 v232, v232, v149
	v_add_f32_e32 v232, v232, v150
	v_add_f32_e32 v232, v232, v151
	v_add_f32_e32 v232, v232, v154
	v_mfma_f32_16x16x32_bf16 v[60:63], v[44:47], v[208:211], v[60:63]
	v_add_f32_e32 v232, v232, v155
	v_add_f32_e32 v232, v232, v156
	v_add_f32_e32 v232, v232, v157
	v_add_f32_e32 v83, v83, v232
	v_cvt_pk_bf16_f32 v212, v140, v141
	v_cvt_pk_bf16_f32 v213, v142, v143
	v_cvt_pk_bf16_f32 v214, v144, v145
	v_cvt_pk_bf16_f32 v215, v146, v147
	v_cvt_pk_bf16_f32 v216, v148, v149
	v_cvt_pk_bf16_f32 v217, v150, v151
	v_cvt_pk_bf16_f32 v218, v154, v155
	v_cvt_pk_bf16_f32 v219, v156, v157
	s_cmp_lt_i32 s15, 0
	s_cbranch_scc1 .Lnsa_brk_4
	s_waitcnt lgkmcnt(0)
	v_mfma_f32_16x16x32_bf16 v[64:67], v[16:19], v[212:215], v[64:67]
	s_lshl_b32 s44, s15, 6
	s_lshl_b32 s65, 1, s15
	v_and_b32_e32 v220, s65, v248
	v_mfma_f32_16x16x32_bf16 v[68:71], v[24:27], v[212:215], v[68:71]
	v_and_b32_e32 v221, s65, v249
	v_cmp_ne_u32_e64 s[60:61], 0, v220
	v_cmp_ne_u32_e64 s[62:63], 0, v221
	v_mfma_f32_16x16x32_bf16 v[72:75], v[32:35], v[212:215], v[72:75]
	s_cmp_eq_u32 s15, s32
	s_cselect_b32 s64, 1, 0
	s_cmp_eq_u32 s15, s14
	v_mfma_f32_16x16x32_bf16 v[76:79], v[40:43], v[212:215], v[76:79]
	s_cselect_b32 s64, 1, s64
	s_xor_b32 s17, s50, 0x4800
	v_add_u32_e32 v244, s17, v114
	v_mfma_f32_16x16x32_bf16 v[64:67], v[20:23], v[216:219], v[64:67]
	v_add_u32_e32 v245, s17, v123
	v_add_u32_e32 v247, s50, v116
	v_cndmask_b32_e64 v228, v227, v80, s[60:61]
	v_mfma_f32_16x16x32_bf16 v[68:71], v[28:31], v[216:219], v[68:71]
	v_cndmask_b32_e64 v229, v227, v80, s[60:61]
	v_cndmask_b32_e64 v230, v227, v80, s[60:61]
	v_cndmask_b32_e64 v231, v227, v80, s[60:61]
	v_mfma_f32_16x16x32_bf16 v[72:75], v[36:39], v[216:219], v[72:75]
	v_cndmask_b32_e64 v236, v227, v81, s[62:63]
	v_cndmask_b32_e64 v237, v227, v81, s[62:63]
	v_cndmask_b32_e64 v238, v227, v81, s[62:63]
	v_mfma_f32_16x16x32_bf16 v[76:79], v[44:47], v[216:219], v[76:79]
	v_cndmask_b32_e64 v239, v227, v81, s[62:63]
	ds_read_b64 v[16:17], v247 offset:9216
	ds_read_b64 v[18:19], v247 offset:9248
	ds_read_b64 v[20:21], v247 offset:9280
	ds_read_b64 v[22:23], v247 offset:9312
	ds_read_b64 v[24:25], v247 offset:11520
	ds_read_b64 v[26:27], v247 offset:11552
	ds_read_b64 v[28:29], v247 offset:11584
	ds_read_b64 v[30:31], v247 offset:11616
	ds_read_b64 v[32:33], v247 offset:13824
	ds_read_b64 v[34:35], v247 offset:13856
	ds_read_b64 v[36:37], v247 offset:13888
	ds_read_b64 v[38:39], v247 offset:13920
	ds_read_b64 v[40:41], v247 offset:16128
	ds_read_b64 v[42:43], v247 offset:16160
	ds_read_b64 v[44:45], v247 offset:16192
	ds_read_b64 v[46:47], v247 offset:16224
	v_mfma_f32_16x16x32_bf16 v[124:127], v[160:163], v[0:3], v[228:231]
	s_waitcnt vmcnt(4)
	ds_write_b128 v244, v[88:91]
	v_mfma_f32_16x16x32_bf16 v[128:131], v[168:171], v[0:3], v[228:231]
	ds_write_b128 v245, v[92:95]
	s_mov_b32 s16, s40
	v_mfma_f32_16x16x32_bf16 v[132:135], v[176:179], v[0:3], v[228:231]
	s_ff1_i32_b32 s40, s38
	s_add_i32 s65, s38, -1
	v_mfma_f32_16x16x32_bf16 v[136:139], v[184:187], v[0:3], v[228:231]
	s_and_b32 s38, s38, s65
	s_max_i32 s65, s40, 0
	v_mfma_f32_16x16x32_bf16 v[124:127], v[164:167], v[4:7], v[124:127]
	s_mul_i32 s56, s65, 0x18000
	s_lshl_b32 s58, s65, 7
	v_mfma_f32_16x16x32_bf16 v[128:131], v[172:175], v[4:7], v[128:131]
	s_add_u32 s56, s46, s56
	s_addc_u32 s57, s47, 0
	v_mfma_f32_16x16x32_bf16 v[132:135], v[180:183], v[4:7], v[132:135]
	s_add_u32 s58, s48, s58
	s_addc_u32 s59, s49, 0
	v_mfma_f32_16x16x32_bf16 v[136:139], v[188:191], v[4:7], v[136:139]
	global_load_dwordx4 v[88:91], v117, s[56:57]
	global_load_dwordx4 v[92:95], v118, s[58:59]
	s_cmp_eq_u32 s64, 0
	s_cbranch_scc1 .Lnsa_nm_17
	v_lshl_add_u32 v222, v113, 2, s44
	v_sub_u32_e32 v120, v86, v222
	v_cndmask_b32_e64 v240, -1, v120, s[60:61]
	v_subrev_u32_e32 v220, 0, v240
	v_subrev_u32_e32 v221, 1, v240
	v_subrev_u32_e32 v222, 2, v240
	v_subrev_u32_e32 v223, 3, v240
	v_cmp_gt_u32_e64 s[52:53], s45, v220
	v_cmp_gt_u32_e64 s[54:55], s45, v221
	v_cmp_gt_u32_e64 s[56:57], s45, v222
	v_cmp_gt_u32_e64 s[58:59], s45, v223
	v_cndmask_b32_e64 v124, v224, v124, s[52:53]
	v_cndmask_b32_e64 v125, v224, v125, s[54:55]
	v_cndmask_b32_e64 v126, v224, v126, s[56:57]
	v_cndmask_b32_e64 v127, v224, v127, s[58:59]
	v_subrev_u32_e32 v220, 16, v240
	v_subrev_u32_e32 v221, 17, v240
	v_subrev_u32_e32 v222, 18, v240
	v_subrev_u32_e32 v223, 19, v240
	v_cmp_gt_u32_e64 s[52:53], s45, v220
	v_cmp_gt_u32_e64 s[54:55], s45, v221
	v_cmp_gt_u32_e64 s[56:57], s45, v222
	v_cmp_gt_u32_e64 s[58:59], s45, v223
	v_cndmask_b32_e64 v128, v224, v128, s[52:53]
	v_cndmask_b32_e64 v129, v224, v129, s[54:55]
	v_cndmask_b32_e64 v130, v224, v130, s[56:57]
	v_cndmask_b32_e64 v131, v224, v131, s[58:59]
	v_subrev_u32_e32 v220, 32, v240
	v_subrev_u32_e32 v221, 33, v240
	v_subrev_u32_e32 v222, 34, v240
	v_subrev_u32_e32 v223, 35, v240
	v_cmp_gt_u32_e64 s[52:53], s45, v220
	v_cmp_gt_u32_e64 s[54:55], s45, v221
	v_cmp_gt_u32_e64 s[56:57], s45, v222
	v_cmp_gt_u32_e64 s[58:59], s45, v223
	v_cndmask_b32_e64 v132, v224, v132, s[52:53]
	v_cndmask_b32_e64 v133, v224, v133, s[54:55]
	v_cndmask_b32_e64 v134, v224, v134, s[56:57]
	v_cndmask_b32_e64 v135, v224, v135, s[58:59]
	v_subrev_u32_e32 v220, 48, v240
	v_subrev_u32_e32 v221, 49, v240
	v_subrev_u32_e32 v222, 50, v240
	v_subrev_u32_e32 v223, 51, v240
	v_cmp_gt_u32_e64 s[52:53], s45, v220
	v_cmp_gt_u32_e64 s[54:55], s45, v221
	v_cmp_gt_u32_e64 s[56:57], s45, v222
	v_cmp_gt_u32_e64 s[58:59], s45, v223
	v_cndmask_b32_e64 v136, v224, v136, s[52:53]
	v_cndmask_b32_e64 v137, v224, v137, s[54:55]
	v_cndmask_b32_e64 v138, v224, v138, s[56:57]
	v_cndmask_b32_e64 v139, v224, v139, s[58:59]

.Lnsa_rb_21:
	s_waitcnt lgkmcnt(0)
	s_barrier
	s_mov_b32 s50, s17
	s_mov_b32 s15, s16
	v_add_u32_e32 v225, s50, v115
	v_add_u32_e32 v246, s50, v122
	ds_read_b128 v[160:163], v225 offset:0
	ds_read_b128 v[168:171], v225 offset:2048
	ds_read_b128 v[176:179], v225 offset:4096
	ds_read_b128 v[184:187], v225 offset:6144
	ds_read_b128 v[164:167], v246 offset:0
	ds_read_b128 v[172:175], v246 offset:2048
	ds_read_b128 v[180:183], v246 offset:4096
	ds_read_b128 v[188:191], v246 offset:6144
	v_mfma_f32_16x16x32_bf16 v[48:51], v[16:19], v[204:207], v[48:51]
	v_exp_f32_e32 v140, v140
	v_exp_f32_e32 v141, v141
	v_exp_f32_e32 v142, v142
	v_exp_f32_e32 v143, v143
	v_mfma_f32_16x16x32_bf16 v[52:55], v[24:27], v[204:207], v[52:55]
	v_exp_f32_e32 v144, v144
	v_exp_f32_e32 v145, v145
	v_exp_f32_e32 v146, v146
	v_exp_f32_e32 v147, v147
	v_mfma_f32_16x16x32_bf16 v[56:59], v[32:35], v[204:207], v[56:59]
	v_exp_f32_e32 v148, v148
	v_exp_f32_e32 v149, v149
	v_exp_f32_e32 v150, v150
	v_exp_f32_e32 v151, v151
	v_mfma_f32_16x16x32_bf16 v[60:63], v[40:43], v[204:207], v[60:63]
	v_exp_f32_e32 v154, v154
	v_exp_f32_e32 v155, v155
	v_exp_f32_e32 v156, v156
	v_exp_f32_e32 v157, v157
	v_mfma_f32_16x16x32_bf16 v[48:51], v[20:23], v[208:211], v[48:51]
	v_add_f32_e32 v232, v140, v141
	v_add_f32_e32 v232, v232, v142
	v_add_f32_e32 v232, v232, v143
	v_add_f32_e32 v232, v232, v144
	v_mfma_f32_16x16x32_bf16 v[52:55], v[28:31], v[208:211], v[52:55]
	v_add_f32_e32 v232, v232, v145
	v_add_f32_e32 v232, v232, v146
	v_add_f32_e32 v232, v232, v147
	v_add_f32_e32 v232, v232, v148
	v_mfma_f32_16x16x32_bf16 v[56:59], v[36:39], v[208:211], v[56:59]
	v_add_f32_e32 v232, v232, v149
	v_add_f32_e32 v232, v232, v150
	v_add_f32_e32 v232, v232, v151
	v_add_f32_e32 v232, v232, v154
	v_mfma_f32_16x16x32_bf16 v[60:63], v[44:47], v[208:211], v[60:63]
	v_add_f32_e32 v232, v232, v155
	v_add_f32_e32 v232, v232, v156
	v_add_f32_e32 v232, v232, v157
	v_add_f32_e32 v83, v83, v232
	v_cvt_pk_bf16_f32 v212, v140, v141
	v_cvt_pk_bf16_f32 v213, v142, v143
	v_cvt_pk_bf16_f32 v214, v144, v145
	v_cvt_pk_bf16_f32 v215, v146, v147
	v_cvt_pk_bf16_f32 v216, v148, v149
	v_cvt_pk_bf16_f32 v217, v150, v151
	v_cvt_pk_bf16_f32 v218, v154, v155
	v_cvt_pk_bf16_f32 v219, v156, v157
	s_branch .Lnsa_loop_3

.Lnsa_brk_4:
	v_mfma_f32_16x16x32_bf16 v[64:67], v[16:19], v[212:215], v[64:67]
	v_mfma_f32_16x16x32_bf16 v[68:71], v[24:27], v[212:215], v[68:71]
	v_mfma_f32_16x16x32_bf16 v[72:75], v[32:35], v[212:215], v[72:75]
	v_mfma_f32_16x16x32_bf16 v[76:79], v[40:43], v[212:215], v[76:79]
	v_mfma_f32_16x16x32_bf16 v[64:67], v[20:23], v[216:219], v[64:67]
	v_mfma_f32_16x16x32_bf16 v[68:71], v[28:31], v[216:219], v[68:71]
	v_mfma_f32_16x16x32_bf16 v[72:75], v[36:39], v[216:219], v[72:75]
	v_mfma_f32_16x16x32_bf16 v[76:79], v[44:47], v[216:219], v[76:79]
	s_waitcnt lgkmcnt(0)
	ds_read_b128 v[124:127], v250 offset:0
	ds_read_b128 v[128:131], v250 offset:1024
	ds_read_b128 v[132:135], v250 offset:2048
	ds_read_b128 v[136:139], v250 offset:3072
	ds_read_b128 v[140:143], v250 offset:4096
	ds_read_b128 v[144:147], v250 offset:5120
	ds_read_b128 v[148:151], v250 offset:6144
	ds_read_b128 v[154:157], v250 offset:7168
	s_nop 7
	s_lshl_b32 s3, s30, 11
	v_mov_b32_e32 v221, v82
	s_nop 1
	v_permlane16_swap_b32_e32 v82, v221
	v_add_f32_e32 v82, v82, v221
	v_mov_b32_e32 v221, v82
	s_nop 1
	v_permlane32_swap_b32_e32 v82, v221
	v_add_f32_e32 v82, v82, v221
	v_max_f32_e32 v220, 0xda24260, v82
	s_cmp_eq_u32 s37, 1
	s_cselect_b64 vcc, -1, 0
	s_nop 1
	v_cndmask_b32_e32 v222, v119, v158, vcc
	v_lshlrev_b32_e32 v222, 16, v222
	v_div_scale_f32 v240, s[52:53], v220, v220, v222
	v_rcp_f32_e32 v241, v240
	v_div_scale_f32 v242, vcc, v222, v220, v222
	v_fma_f32 v243, -v240, v241, 1.0
	v_fmac_f32_e32 v241, v243, v241
	v_mul_f32_e32 v243, v242, v241
	v_fma_f32 v244, -v240, v243, v242
	v_fmac_f32_e32 v243, v244, v241
	v_fma_f32 v240, -v240, v243, v242
	s_nop 1
	v_div_fmas_f32 v240, v240, v241, v243
	v_div_fixup_f32 v228, v240, v220, v222
	s_waitcnt lgkmcnt(0)
	v_pk_fma_f32 v[124:125], v[48:49], v[228:229], v[124:125] op_sel_hi:[1,0,1]
	v_pk_fma_f32 v[126:127], v[50:51], v[228:229], v[126:127] op_sel_hi:[1,0,1]
	v_pk_fma_f32 v[128:129], v[52:53], v[228:229], v[128:129] op_sel_hi:[1,0,1]
	v_pk_fma_f32 v[130:131], v[54:55], v[228:229], v[130:131] op_sel_hi:[1,0,1]
	v_pk_fma_f32 v[132:133], v[56:57], v[228:229], v[132:133] op_sel_hi:[1,0,1]
	v_pk_fma_f32 v[134:135], v[58:59], v[228:229], v[134:135] op_sel_hi:[1,0,1]
	v_pk_fma_f32 v[136:137], v[60:61], v[228:229], v[136:137] op_sel_hi:[1,0,1]
	v_pk_fma_f32 v[138:139], v[62:63], v[228:229], v[138:139] op_sel_hi:[1,0,1]
	ds_write_b128 v250, v[124:127] offset:0
	ds_write_b128 v250, v[128:131] offset:1024
	ds_write_b128 v250, v[132:135] offset:2048
	ds_write_b128 v250, v[136:139] offset:3072
	v_mov_b32_e32 v221, v83
	s_nop 1
	v_permlane16_swap_b32_e32 v83, v221
	v_add_f32_e32 v83, v83, v221
	v_mov_b32_e32 v221, v83
	s_nop 1
	v_permlane32_swap_b32_e32 v83, v221
	v_add_f32_e32 v83, v83, v221
	v_max_f32_e32 v220, 0xda24260, v83
	s_cmp_eq_u32 s37, 1
	s_cselect_b64 vcc, -1, 0
	s_nop 1
	v_cndmask_b32_e32 v222, v159, v233, vcc
	v_lshlrev_b32_e32 v222, 16, v222
	v_div_scale_f32 v240, s[52:53], v220, v220, v222
	v_rcp_f32_e32 v241, v240
	v_div_scale_f32 v242, vcc, v222, v220, v222
	v_fma_f32 v243, -v240, v241, 1.0
	v_fmac_f32_e32 v241, v243, v241
	v_mul_f32_e32 v243, v242, v241
	v_fma_f32 v244, -v240, v243, v242
	v_fmac_f32_e32 v243, v244, v241
	v_fma_f32 v240, -v240, v243, v242
	s_nop 1
	v_div_fmas_f32 v240, v240, v241, v243
	v_div_fixup_f32 v228, v240, v220, v222
	v_pk_fma_f32 v[140:141], v[64:65], v[228:229], v[140:141] op_sel_hi:[1,0,1]
	v_pk_fma_f32 v[142:143], v[66:67], v[228:229], v[142:143] op_sel_hi:[1,0,1]
	v_pk_fma_f32 v[144:145], v[68:69], v[228:229], v[144:145] op_sel_hi:[1,0,1]
	v_pk_fma_f32 v[146:147], v[70:71], v[228:229], v[146:147] op_sel_hi:[1,0,1]
	v_pk_fma_f32 v[148:149], v[72:73], v[228:229], v[148:149] op_sel_hi:[1,0,1]
	v_pk_fma_f32 v[150:151], v[74:75], v[228:229], v[150:151] op_sel_hi:[1,0,1]
	v_pk_fma_f32 v[154:155], v[76:77], v[228:229], v[154:155] op_sel_hi:[1,0,1]
	v_pk_fma_f32 v[156:157], v[78:79], v[228:229], v[156:157] op_sel_hi:[1,0,1]
	ds_write_b128 v250, v[140:143] offset:4096
	ds_write_b128 v250, v[144:147] offset:5120
	ds_write_b128 v250, v[148:151] offset:6144
	ds_write_b128 v250, v[154:157] offset:7168
	s_add_i32 s37, s37, 1
	s_cmp_lt_u32 s37, 2
	s_cbranch_scc1 .Lnsa_br
	s_lshl_b32 s3, s30, 11
	s_add_u32 s8, s96, 0x9000000
	s_addc_u32 s9, s97, 0
	v_add_u32_e32 v223, s3, v86
	v_lshlrev_b32_e32 v223, 10, v223
	s_lshl_b32 s2, s36, 7
	v_add_u32_e32 v223, s2, v223
	v_lshl_add_u32 v223, v113, 3, v223
	v_cvt_pk_bf16_f32 v240, v124, v125
	v_cvt_pk_bf16_f32 v241, v126, v127
	global_store_dwordx2 v223, v[240:241], s[8:9] offset:0
	v_cvt_pk_bf16_f32 v240, v128, v129
	v_cvt_pk_bf16_f32 v241, v130, v131
	global_store_dwordx2 v223, v[240:241], s[8:9] offset:32
	v_cvt_pk_bf16_f32 v240, v132, v133
	v_cvt_pk_bf16_f32 v241, v134, v135
	global_store_dwordx2 v223, v[240:241], s[8:9] offset:64
	v_cvt_pk_bf16_f32 v240, v136, v137
	v_cvt_pk_bf16_f32 v241, v138, v139
	global_store_dwordx2 v223, v[240:241], s[8:9] offset:96
	v_add_u32_e32 v223, s3, v87
	v_lshlrev_b32_e32 v223, 10, v223
	s_lshl_b32 s2, s36, 7
	v_add_u32_e32 v223, s2, v223
	v_lshl_add_u32 v223, v113, 3, v223
	v_cvt_pk_bf16_f32 v240, v140, v141
	v_cvt_pk_bf16_f32 v241, v142, v143
	global_store_dwordx2 v223, v[240:241], s[8:9] offset:0
	v_cvt_pk_bf16_f32 v240, v144, v145
	v_cvt_pk_bf16_f32 v241, v146, v147
	global_store_dwordx2 v223, v[240:241], s[8:9] offset:32
	v_cvt_pk_bf16_f32 v240, v148, v149
	v_cvt_pk_bf16_f32 v241, v150, v151
	global_store_dwordx2 v223, v[240:241], s[8:9] offset:64
	v_cvt_pk_bf16_f32 v240, v154, v155
	v_cvt_pk_bf16_f32 v241, v156, v157
	global_store_dwordx2 v223, v[240:241], s[8:9] offset:96
	s_add_i32 s26, s26, s92
	s_cmpk_lt_i32 s26, 0x400
	s_cbranch_scc1 .Lnsa_task
